# out-proj epilogue: residual loads non-temporal in layer 0 only (x is cold and read for the last time), default in layer 1
# baseline (speedup 1.0000x reference)
.LBB0_331:
	s_add_i32 s2, s70, 5
	v_readlane_b32 s24, v254, 1
	s_cmp_gt_u32 s2, 12
	v_readlane_b32 s25, v254, 2
	s_cselect_b64 s[38:39], -1, 0
	s_cmp_lt_u32 s2, 13
	v_readlane_b32 s30, v254, 7
	v_readlane_b32 s31, v254, 8
	s_mov_b64 s[24:25], s[64:65]
	s_cselect_b32 s37, s45, s31
	s_cselect_b32 s36, s44, s30
	s_lshl_b32 s2, s24, 10
	s_ashr_i32 s3, s2, 31
	v_readlane_b32 s26, v254, 3
	s_lshl_b64 s[2:3], s[2:3], 2
	v_readlane_b32 s27, v254, 4
	s_add_u32 s4, s26, s2
	v_readlane_b32 s28, v254, 5
	s_addc_u32 s5, s27, s3
	v_readlane_b32 s29, v254, 6
	s_add_u32 s2, s28, s2
	v_and_b32_e32 v163, 64, v210
	s_addc_u32 s3, s29, s3
	s_lshl_b32 s6, s21, 5
	s_lshl_b32 s7, s9, 8
	v_xor_b32_e32 v162, 16, v210
	v_add_u32_e32 v163, 64, v163
	s_or_b32 s6, s7, s6
	v_lshrrev_b32_e32 v0, 2, v10
	v_cmp_lt_i32_e32 vcc, v162, v163
	v_and_or_b32 v160, v0, 12, s6
	v_ashrrev_i32_e32 v161, 31, v160
	v_cndmask_b32_e32 v162, v210, v162, vcc
	v_lshlrev_b32_e32 v194, 2, v162
	v_xor_b32_e32 v162, 32, v210
	v_lshlrev_b64 v[164:165], 2, v[160:161]
	v_cmp_lt_i32_e32 vcc, v162, v163
	s_lshl_b32 s5, s82, 8
	v_cndmask_b32_e32 v162, v210, v162, vcc
	v_lshlrev_b32_e32 v193, 2, v162
	v_add_u32_e32 v162, s5, v192
	v_ashrrev_i32_e32 v163, 31, v162
	v_lshlrev_b64 v[166:167], 12, v[162:163]
	v_lshl_add_u64 v[166:167], s[36:37], 0, v[166:167]
	v_lshl_add_u64 v[190:191], v[166:167], 0, v[164:165]
	v_and_b32_e32 v176, 63, v10
	s_barrier
	v_add_u32_e32 v252, s5, v192
	v_lshlrev_b32_e32 v252, 12, v252
	v_lshl_add_u32 v252, v160, 2, v252
	s_cmp_eq_u64 s[38:39], 0
	s_cbranch_scc0 .Lr1_plain
	global_load_dwordx4 v[0:3], v252, s[36:37] nt
	global_load_dwordx4 v[4:7], v252, s[36:37] offset:64 nt
	global_load_dwordx4 v[8:11], v252, s[36:37] offset:512 nt
	global_load_dwordx4 v[12:15], v252, s[36:37] offset:576 nt
	s_branch .Lr1_done
.Lr1_plain:
	global_load_dwordx4 v[0:3], v252, s[36:37]
	global_load_dwordx4 v[4:7], v252, s[36:37] offset:64
	global_load_dwordx4 v[8:11], v252, s[36:37] offset:512
	global_load_dwordx4 v[12:15], v252, s[36:37] offset:576
.Lr1_done:
	v_add_u32_e32 v253, 0x10000, v252
	s_cmp_eq_u64 s[38:39], 0
	s_cbranch_scc0 .Lr2_plain
	global_load_dwordx4 v[16:19], v253, s[36:37] nt
	global_load_dwordx4 v[20:23], v253, s[36:37] offset:64 nt
	global_load_dwordx4 v[24:27], v253, s[36:37] offset:512 nt
	global_load_dwordx4 v[28:31], v253, s[36:37] offset:576 nt
	s_branch .Lr2_done
.Lr2_plain:
	global_load_dwordx4 v[16:19], v253, s[36:37]
	global_load_dwordx4 v[20:23], v253, s[36:37] offset:64
	global_load_dwordx4 v[24:27], v253, s[36:37] offset:512
	global_load_dwordx4 v[28:31], v253, s[36:37] offset:576
.Lr2_done:
	v_add_u32_e32 v253, 0x20000, v252
	s_cmp_eq_u64 s[38:39], 0
	s_cbranch_scc0 .Lr3_plain
	global_load_dwordx4 v[244:247], v253, s[36:37] nt
	global_load_dwordx4 v[248:251], v253, s[36:37] offset:64 nt
	global_load_dwordx4 v[178:181], v253, s[36:37] offset:512 nt
	global_load_dwordx4 v[182:185], v253, s[36:37] offset:576 nt
	s_branch .Lr3_done
.Lr3_plain:
	global_load_dwordx4 v[244:247], v253, s[36:37]
	global_load_dwordx4 v[248:251], v253, s[36:37] offset:64
	global_load_dwordx4 v[178:181], v253, s[36:37] offset:512
	global_load_dwordx4 v[182:185], v253, s[36:37] offset:576
.Lr3_done:
	s_mov_b32 s2, 0x3fb504f3
	v_cmp_gt_u32_e32 vcc, 16, v176
	s_lshl_b32 s4, s21, 3
	s_waitcnt vmcnt(8)
	v_pk_fma_f32 v[158:159], v[2:3], s[2:3], v[158:159] op_sel_hi:[1,0,1]
	v_pk_fma_f32 v[154:155], v[6:7], s[2:3], v[154:155] op_sel_hi:[1,0,1]
	v_pk_fma_f32 v[152:153], v[4:5], s[2:3], v[152:153] op_sel_hi:[1,0,1]
	v_pk_fma_f32 v[156:157], v[0:1], s[2:3], v[156:157] op_sel_hi:[1,0,1]
	v_mul_f32_e32 v169, v158, v158
	v_mul_f32_e32 v168, v154, v154
	v_add_f32_e32 v164, v156, v157
	v_add_f32_e32 v166, v158, v159
	v_mul_f32_e32 v173, v156, v156
	v_mul_f32_e32 v175, v157, v157
	v_mul_f32_e32 v171, v159, v159
	v_mul_f32_e32 v165, v152, v152
	v_mul_f32_e32 v167, v153, v153
	v_pk_fma_f32 v[196:197], v[154:155], v[154:155], v[168:169] op_sel_hi:[1,1,0]
	v_mov_b32_e32 v172, v152
	v_mov_b32_e32 v174, v153
	v_mov_b32_e32 v168, v154
	v_mov_b32_e32 v170, v155
	v_pk_add_f32 v[172:173], v[172:173], v[174:175]
	v_pk_add_f32 v[168:169], v[168:169], v[170:171]
	v_pk_add_f32 v[164:165], v[164:165], v[166:167]
	v_mov_b32_e32 v196, v177
	v_pk_add_f32 v[168:169], v[172:173], v[168:169]
	v_pk_add_f32 v[164:165], v[164:165], v[196:197]
	v_pk_fma_f32 v[150:151], v[10:11], s[2:3], v[150:151] op_sel_hi:[1,0,1]
	v_pk_fma_f32 v[148:149], v[8:9], s[2:3], v[148:149] op_sel_hi:[1,0,1]
	v_mul_f32_e32 v199, v148, v148
	v_mul_f32_e32 v201, v149, v149
	v_mul_f32_e32 v203, v150, v150
	v_mul_f32_e32 v205, v151, v151
	v_mov_b32_e32 v198, v148
	v_mov_b32_e32 v200, v149
	v_mov_b32_e32 v202, v150
	v_mov_b32_e32 v204, v151
	v_pk_add_f32 v[164:165], v[168:169], v[164:165]
	v_pk_add_f32 v[166:167], v[198:199], v[200:201]
	v_pk_add_f32 v[168:169], v[202:203], v[204:205]
	v_pk_fma_f32 v[146:147], v[14:15], s[2:3], v[146:147] op_sel_hi:[1,0,1]
	v_pk_fma_f32 v[144:145], v[12:13], s[2:3], v[144:145] op_sel_hi:[1,0,1]
	v_add_u32_e32 v253, 0x30000, v252
	s_cmp_eq_u64 s[38:39], 0
	s_cbranch_scc0 .Lr4_plain
	global_load_dwordx4 v[0:3], v253, s[36:37] nt
	global_load_dwordx4 v[4:7], v253, s[36:37] offset:64 nt
	global_load_dwordx4 v[8:11], v253, s[36:37] offset:512 nt
	global_load_dwordx4 v[12:15], v253, s[36:37] offset:576 nt
	s_branch .Lr4_done
.Lr4_plain:
	global_load_dwordx4 v[0:3], v253, s[36:37]
	global_load_dwordx4 v[4:7], v253, s[36:37] offset:64
	global_load_dwordx4 v[8:11], v253, s[36:37] offset:512
	global_load_dwordx4 v[12:15], v253, s[36:37] offset:576
.Lr4_done:
	v_mul_f32_e32 v191, v146, v146
	v_mul_f32_e32 v187, v144, v144
	v_mul_f32_e32 v189, v145, v145
	v_mul_f32_e32 v215, v147, v147
	v_pk_add_f32 v[166:167], v[166:167], v[168:169]
	v_mov_b32_e32 v186, v144
	v_mov_b32_e32 v188, v145
	v_mov_b32_e32 v190, v146
	v_mov_b32_e32 v214, v147
	v_pk_add_f32 v[164:165], v[164:165], v[166:167]
	v_pk_add_f32 v[166:167], v[186:187], v[188:189]
	v_pk_add_f32 v[168:169], v[190:191], v[214:215]
	s_nop 0
	v_pk_add_f32 v[166:167], v[166:167], v[168:169]
	s_nop 0
	v_pk_add_f32 v[164:165], v[164:165], v[166:167]
	ds_bpermute_b32 v166, v194, v164
	ds_bpermute_b32 v167, v194, v165
	s_waitcnt lgkmcnt(0)
	v_pk_add_f32 v[164:165], v[164:165], v[166:167]
	ds_bpermute_b32 v166, v193, v164
	ds_bpermute_b32 v167, v193, v165
	s_and_saveexec_b64 s[2:3], vcc
	v_readlane_b32 s60, v255, 42
	v_readlane_b32 s62, v255, 44
	v_readlane_b32 s64, v255, 46
	v_readlane_b32 s74, v255, 48
	v_readlane_b32 s34, v255, 38
	v_readlane_b32 s42, v255, 41
	v_readlane_b32 s61, v255, 43
	v_readlane_b32 s63, v255, 45
	v_readlane_b32 s65, v255, 47
	v_readlane_b32 s75, v255, 49
	v_readlane_b32 s43, v255, 50
	v_readlane_b32 s35, v255, 39
	s_cbranch_execz .LBB0_333
	v_lshl_or_b32 v168, v192, 5, s4
	s_waitcnt lgkmcnt(0)
	v_pk_add_f32 v[164:165], v[164:165], v[166:167]
	ds_write_b64 v168, v[164:165]
.LBB0_333:
	s_or_b64 exec, exec, s[2:3]
	v_or_b32_e32 v196, 16, v192
	v_add_u32_e32 v164, s5, v196
	v_ashrrev_i32_e32 v165, 31, v164
	s_waitcnt lgkmcnt(0)
	v_lshlrev_b64 v[166:167], 12, v[164:165]
	v_lshl_add_u64 v[166:167], s[36:37], 0, v[166:167]
	v_lshl_add_u64 v[170:171], v[160:161], 2, v[166:167]
	s_mov_b32 s2, 0x3fb504f3
	s_waitcnt vmcnt(8)
	v_pk_fma_f32 v[142:143], v[18:19], s[2:3], v[142:143] op_sel_hi:[1,0,1]
	v_pk_fma_f32 v[140:141], v[16:17], s[2:3], v[140:141] op_sel_hi:[1,0,1]
	v_add_f32_e32 v172, v140, v141
	v_add_f32_e32 v174, v142, v143
	v_mul_f32_e32 v187, v140, v140
	v_mul_f32_e32 v189, v141, v141
	v_mul_f32_e32 v191, v142, v142
	v_mul_f32_e32 v199, v143, v143
	v_pk_fma_f32 v[138:139], v[22:23], s[2:3], v[138:139] op_sel_hi:[1,0,1]
	v_pk_fma_f32 v[136:137], v[20:21], s[2:3], v[136:137] op_sel_hi:[1,0,1]
	v_mul_f32_e32 v166, v138, v138
	v_pk_fma_f32 v[200:201], v[138:139], v[138:139], v[166:167] op_sel_hi:[1,1,0]
	v_mul_f32_e32 v173, v136, v136
	v_mul_f32_e32 v175, v137, v137
	v_mov_b32_e32 v186, v136
	v_mov_b32_e32 v188, v137
	v_mov_b32_e32 v190, v138
	v_mov_b32_e32 v198, v139
	v_pk_add_f32 v[186:187], v[186:187], v[188:189]
	v_pk_add_f32 v[188:189], v[190:191], v[198:199]
	v_pk_add_f32 v[172:173], v[172:173], v[174:175]
	v_mov_b32_e32 v200, v177
	v_pk_add_f32 v[186:187], v[186:187], v[188:189]
	v_pk_add_f32 v[172:173], v[172:173], v[200:201]
	v_pk_fma_f32 v[134:135], v[26:27], s[2:3], v[134:135] op_sel_hi:[1,0,1]
	v_pk_fma_f32 v[132:133], v[24:25], s[2:3], v[132:133] op_sel_hi:[1,0,1]
	v_mul_f32_e32 v203, v132, v132
	v_mul_f32_e32 v205, v133, v133
	v_mul_f32_e32 v215, v134, v134
	v_mul_f32_e32 v221, v135, v135
	v_mov_b32_e32 v202, v132
	v_mov_b32_e32 v204, v133
	v_mov_b32_e32 v214, v134
	v_mov_b32_e32 v220, v135
	v_pk_add_f32 v[172:173], v[186:187], v[172:173]
	v_pk_add_f32 v[174:175], v[202:203], v[204:205]
	v_pk_add_f32 v[186:187], v[214:215], v[220:221]
	v_pk_fma_f32 v[130:131], v[30:31], s[2:3], v[130:131] op_sel_hi:[1,0,1]
	v_pk_fma_f32 v[128:129], v[28:29], s[2:3], v[128:129] op_sel_hi:[1,0,1]
	v_add_u32_e32 v253, 0x80000, v252
	s_cmp_eq_u64 s[38:39], 0
	s_cbranch_scc0 .Lr5_plain
	global_load_dwordx4 v[16:19], v253, s[36:37] nt
	global_load_dwordx4 v[20:23], v253, s[36:37] offset:64 nt
	global_load_dwordx4 v[24:27], v253, s[36:37] offset:512 nt
	global_load_dwordx4 v[28:31], v253, s[36:37] offset:576 nt
	s_branch .Lr5_done

.Lr5_done:
	v_mul_f32_e32 v171, v130, v130
	v_mul_f32_e32 v167, v128, v128
	v_mul_f32_e32 v169, v129, v129
	v_mul_f32_e32 v223, v131, v131
	v_mov_b32_e32 v166, v128
	v_mov_b32_e32 v168, v129
	v_mov_b32_e32 v170, v130
	v_mov_b32_e32 v222, v131
	v_pk_add_f32 v[174:175], v[174:175], v[186:187]
	v_pk_add_f32 v[166:167], v[166:167], v[168:169]
	v_pk_add_f32 v[168:169], v[170:171], v[222:223]
	v_pk_add_f32 v[172:173], v[172:173], v[174:175]
	v_pk_add_f32 v[166:167], v[166:167], v[168:169]
	s_nop 0
	v_pk_add_f32 v[166:167], v[172:173], v[166:167]
	ds_bpermute_b32 v168, v194, v166
	ds_bpermute_b32 v169, v194, v167
	s_waitcnt lgkmcnt(0)
	v_pk_add_f32 v[166:167], v[166:167], v[168:169]
	ds_bpermute_b32 v168, v193, v166
	ds_bpermute_b32 v169, v193, v167
	s_and_saveexec_b64 s[2:3], vcc
	v_readlane_b32 s35, v255, 40
	s_movk_i32 s26, 0x1ff
	s_cbranch_execz .LBB0_335
	v_lshl_or_b32 v170, v196, 5, s4
	s_waitcnt lgkmcnt(0)
	v_pk_add_f32 v[166:167], v[166:167], v[168:169]
	ds_write_b64 v170, v[166:167]
.LBB0_335:
	s_or_b64 exec, exec, s[2:3]
	v_or_b32_e32 v197, 32, v192
	v_add_u32_e32 v166, s5, v197
	v_ashrrev_i32_e32 v167, 31, v166
	s_waitcnt lgkmcnt(0)
	v_lshlrev_b64 v[168:169], 12, v[166:167]
	v_lshl_add_u64 v[168:169], s[36:37], 0, v[168:169]
	v_lshl_add_u64 v[172:173], v[160:161], 2, v[168:169]
	s_mov_b32 s2, 0x3fb504f3
	s_waitcnt vmcnt(8)
	v_pk_fma_f32 v[126:127], v[246:247], s[2:3], v[126:127] op_sel_hi:[1,0,1]
	v_pk_fma_f32 v[124:125], v[244:245], s[2:3], v[124:125] op_sel_hi:[1,0,1]
	v_add_f32_e32 v174, v124, v125
	v_add_f32_e32 v186, v126, v127
	v_mul_f32_e32 v189, v124, v124
	v_mul_f32_e32 v191, v125, v125
	v_mul_f32_e32 v199, v126, v126
	v_mul_f32_e32 v201, v127, v127
	v_pk_fma_f32 v[122:123], v[250:251], s[2:3], v[122:123] op_sel_hi:[1,0,1]
	v_pk_fma_f32 v[120:121], v[248:249], s[2:3], v[120:121] op_sel_hi:[1,0,1]
	v_mul_f32_e32 v168, v122, v122
	v_pk_fma_f32 v[202:203], v[122:123], v[122:123], v[168:169] op_sel_hi:[1,1,0]
	v_mul_f32_e32 v175, v120, v120
	v_mul_f32_e32 v187, v121, v121
	v_mov_b32_e32 v188, v120
	v_mov_b32_e32 v190, v121
	v_mov_b32_e32 v198, v122
	v_mov_b32_e32 v200, v123
	v_pk_add_f32 v[188:189], v[188:189], v[190:191]
	v_pk_add_f32 v[190:191], v[198:199], v[200:201]
	v_pk_add_f32 v[174:175], v[174:175], v[186:187]
	v_mov_b32_e32 v202, v177
	v_pk_add_f32 v[188:189], v[188:189], v[190:191]
	v_pk_add_f32 v[174:175], v[174:175], v[202:203]
	v_pk_fma_f32 v[118:119], v[180:181], s[2:3], v[118:119] op_sel_hi:[1,0,1]
	v_pk_fma_f32 v[116:117], v[178:179], s[2:3], v[116:117] op_sel_hi:[1,0,1]
	v_mul_f32_e32 v205, v116, v116
	v_mul_f32_e32 v215, v117, v117
	v_mul_f32_e32 v221, v118, v118
	v_mul_f32_e32 v223, v119, v119
	v_mov_b32_e32 v204, v116
	v_mov_b32_e32 v214, v117
	v_mov_b32_e32 v220, v118
	v_mov_b32_e32 v222, v119
	v_pk_add_f32 v[174:175], v[188:189], v[174:175]
	v_pk_add_f32 v[186:187], v[204:205], v[214:215]
	v_pk_add_f32 v[188:189], v[220:221], v[222:223]
	v_pk_fma_f32 v[114:115], v[184:185], s[2:3], v[114:115] op_sel_hi:[1,0,1]
	v_pk_fma_f32 v[112:113], v[182:183], s[2:3], v[112:113] op_sel_hi:[1,0,1]
	v_add_u32_e32 v253, 0x90000, v252
	s_cmp_eq_u64 s[38:39], 0
	s_cbranch_scc0 .Lr6_plain
	global_load_dwordx4 v[244:247], v253, s[36:37] nt
	global_load_dwordx4 v[248:251], v253, s[36:37] offset:64 nt
	global_load_dwordx4 v[178:181], v253, s[36:37] offset:512 nt
	global_load_dwordx4 v[182:185], v253, s[36:37] offset:576 nt
	s_branch .Lr6_done

.Lr6_done:
	v_mul_f32_e32 v173, v114, v114
	v_mul_f32_e32 v169, v112, v112
	v_mul_f32_e32 v171, v113, v113
	v_mul_f32_e32 v225, v115, v115
	v_mov_b32_e32 v168, v112
	v_mov_b32_e32 v170, v113
	v_mov_b32_e32 v172, v114
	v_mov_b32_e32 v224, v115
	v_pk_add_f32 v[186:187], v[186:187], v[188:189]
	v_pk_add_f32 v[168:169], v[168:169], v[170:171]
	v_pk_add_f32 v[170:171], v[172:173], v[224:225]
	v_pk_add_f32 v[174:175], v[174:175], v[186:187]
	v_pk_add_f32 v[168:169], v[168:169], v[170:171]
	s_nop 0
	v_pk_add_f32 v[168:169], v[174:175], v[168:169]
	ds_bpermute_b32 v170, v194, v168
	ds_bpermute_b32 v171, v194, v169
	s_waitcnt lgkmcnt(0)
	v_pk_add_f32 v[168:169], v[168:169], v[170:171]
	ds_bpermute_b32 v170, v193, v168
	ds_bpermute_b32 v171, v193, v169
	s_and_saveexec_b64 s[2:3], vcc
	s_cbranch_execz .LBB0_337
	v_lshl_or_b32 v172, v197, 5, s4
	s_waitcnt lgkmcnt(0)
	v_pk_add_f32 v[168:169], v[168:169], v[170:171]
	ds_write_b64 v172, v[168:169]
.LBB0_337:
	s_or_b64 exec, exec, s[2:3]
	v_or_b32_e32 v198, 48, v192
	v_add_u32_e32 v168, s5, v198
	v_ashrrev_i32_e32 v169, 31, v168
	s_waitcnt lgkmcnt(0)
	v_lshlrev_b64 v[170:171], 12, v[168:169]
	v_lshl_add_u64 v[170:171], s[36:37], 0, v[170:171]
	v_lshl_add_u64 v[174:175], v[160:161], 2, v[170:171]
	s_mov_b32 s2, 0x3fb504f3
	s_waitcnt vmcnt(8)
	v_pk_fma_f32 v[110:111], v[2:3], s[2:3], v[110:111] op_sel_hi:[1,0,1]
	v_pk_fma_f32 v[108:109], v[0:1], s[2:3], v[108:109] op_sel_hi:[1,0,1]
	v_add_f32_e32 v186, v108, v109
	v_add_f32_e32 v188, v110, v111
	v_mul_f32_e32 v191, v108, v108
	v_mul_f32_e32 v201, v109, v109
	v_mul_f32_e32 v203, v110, v110
	v_mul_f32_e32 v205, v111, v111
	v_pk_fma_f32 v[106:107], v[6:7], s[2:3], v[106:107] op_sel_hi:[1,0,1]
	v_pk_fma_f32 v[104:105], v[4:5], s[2:3], v[104:105] op_sel_hi:[1,0,1]
	v_mul_f32_e32 v170, v106, v106
	v_pk_fma_f32 v[214:215], v[106:107], v[106:107], v[170:171] op_sel_hi:[1,1,0]
	v_mul_f32_e32 v187, v104, v104
	v_mul_f32_e32 v189, v105, v105
	v_mov_b32_e32 v190, v104
	v_mov_b32_e32 v200, v105
	v_mov_b32_e32 v202, v106
	v_mov_b32_e32 v204, v107
	v_pk_add_f32 v[190:191], v[190:191], v[200:201]
	v_pk_add_f32 v[200:201], v[202:203], v[204:205]
	v_pk_add_f32 v[186:187], v[186:187], v[188:189]
	v_mov_b32_e32 v214, v177
	v_pk_add_f32 v[190:191], v[190:191], v[200:201]
	v_pk_add_f32 v[186:187], v[186:187], v[214:215]
	v_pk_fma_f32 v[102:103], v[10:11], s[2:3], v[102:103] op_sel_hi:[1,0,1]
	v_pk_fma_f32 v[100:101], v[8:9], s[2:3], v[100:101] op_sel_hi:[1,0,1]
	v_mul_f32_e32 v221, v100, v100
	v_mul_f32_e32 v223, v101, v101
	v_mul_f32_e32 v225, v102, v102
	v_mul_f32_e32 v227, v103, v103
	v_mov_b32_e32 v220, v100
	v_mov_b32_e32 v222, v101
	v_mov_b32_e32 v224, v102
	v_mov_b32_e32 v226, v103
	v_pk_add_f32 v[186:187], v[190:191], v[186:187]
	v_pk_add_f32 v[188:189], v[220:221], v[222:223]
	v_pk_add_f32 v[190:191], v[224:225], v[226:227]
	v_pk_fma_f32 v[98:99], v[14:15], s[2:3], v[98:99] op_sel_hi:[1,0,1]
	v_pk_fma_f32 v[96:97], v[12:13], s[2:3], v[96:97] op_sel_hi:[1,0,1]
	v_add_u32_e32 v253, 0xa0000, v252
	s_cmp_eq_u64 s[38:39], 0
	s_cbranch_scc0 .Lr7_plain
	global_load_dwordx4 v[0:3], v253, s[36:37] nt
	global_load_dwordx4 v[4:7], v253, s[36:37] offset:64 nt
	global_load_dwordx4 v[8:11], v253, s[36:37] offset:512 nt
	global_load_dwordx4 v[12:15], v253, s[36:37] offset:576 nt
	s_branch .Lr7_done

.Lr7_done:
	v_mul_f32_e32 v175, v98, v98
	v_mul_f32_e32 v171, v96, v96
	v_mul_f32_e32 v173, v97, v97
	v_mul_f32_e32 v229, v99, v99
	v_mov_b32_e32 v170, v96
	v_mov_b32_e32 v172, v97
	v_mov_b32_e32 v174, v98
	v_mov_b32_e32 v228, v99
	v_pk_add_f32 v[188:189], v[188:189], v[190:191]
	v_pk_add_f32 v[170:171], v[170:171], v[172:173]
	v_pk_add_f32 v[172:173], v[174:175], v[228:229]
	v_pk_add_f32 v[186:187], v[186:187], v[188:189]
	v_pk_add_f32 v[170:171], v[170:171], v[172:173]
	s_nop 0
	v_pk_add_f32 v[170:171], v[186:187], v[170:171]
	ds_bpermute_b32 v172, v194, v170
	ds_bpermute_b32 v173, v194, v171
	s_waitcnt lgkmcnt(0)
	v_pk_add_f32 v[170:171], v[170:171], v[172:173]
	ds_bpermute_b32 v172, v193, v170
	ds_bpermute_b32 v173, v193, v171
	s_and_saveexec_b64 s[2:3], vcc
	s_cbranch_execz .LBB0_339
	v_lshl_or_b32 v174, v198, 5, s4
	s_waitcnt lgkmcnt(0)
	v_pk_add_f32 v[170:171], v[170:171], v[172:173]
	ds_write_b64 v174, v[170:171]
.LBB0_339:
	s_or_b64 exec, exec, s[2:3]
	v_add_u32_e32 v199, 0x80, v192
	v_add_u32_e32 v170, s5, v199
	v_ashrrev_i32_e32 v171, 31, v170
	s_waitcnt lgkmcnt(0)
	v_lshlrev_b64 v[172:173], 12, v[170:171]
	v_lshl_add_u64 v[172:173], s[36:37], 0, v[172:173]
	v_lshl_add_u64 v[186:187], v[160:161], 2, v[172:173]
	s_mov_b32 s2, 0x3fb504f3
	s_waitcnt vmcnt(8)
	v_pk_fma_f32 v[94:95], v[18:19], s[2:3], v[94:95] op_sel_hi:[1,0,1]
	v_pk_fma_f32 v[92:93], v[16:17], s[2:3], v[92:93] op_sel_hi:[1,0,1]
	v_add_f32_e32 v188, v92, v93
	v_add_f32_e32 v190, v94, v95
	v_mul_f32_e32 v201, v92, v92
	v_mul_f32_e32 v203, v93, v93
	v_mul_f32_e32 v205, v94, v94
	v_mul_f32_e32 v215, v95, v95
	v_pk_fma_f32 v[90:91], v[22:23], s[2:3], v[90:91] op_sel_hi:[1,0,1]
	v_pk_fma_f32 v[88:89], v[20:21], s[2:3], v[88:89] op_sel_hi:[1,0,1]
	v_mul_f32_e32 v172, v90, v90
	v_pk_fma_f32 v[220:221], v[90:91], v[90:91], v[172:173] op_sel_hi:[1,1,0]
	v_mul_f32_e32 v189, v88, v88
	v_mul_f32_e32 v191, v89, v89
	v_mov_b32_e32 v200, v88
	v_mov_b32_e32 v202, v89
	v_mov_b32_e32 v204, v90
	v_mov_b32_e32 v214, v91
	v_pk_add_f32 v[200:201], v[200:201], v[202:203]
	v_pk_add_f32 v[202:203], v[204:205], v[214:215]
	v_pk_add_f32 v[188:189], v[188:189], v[190:191]
	v_mov_b32_e32 v220, v177
	v_pk_add_f32 v[200:201], v[200:201], v[202:203]
	v_pk_add_f32 v[188:189], v[188:189], v[220:221]
	v_pk_fma_f32 v[86:87], v[26:27], s[2:3], v[86:87] op_sel_hi:[1,0,1]
	v_pk_fma_f32 v[84:85], v[24:25], s[2:3], v[84:85] op_sel_hi:[1,0,1]
	v_mul_f32_e32 v223, v84, v84
	v_mul_f32_e32 v225, v85, v85
	v_mul_f32_e32 v227, v86, v86
	v_mul_f32_e32 v229, v87, v87
	v_mov_b32_e32 v222, v84
	v_mov_b32_e32 v224, v85
	v_mov_b32_e32 v226, v86
	v_mov_b32_e32 v228, v87
	v_pk_add_f32 v[188:189], v[200:201], v[188:189]
	v_pk_add_f32 v[190:191], v[222:223], v[224:225]
	v_pk_add_f32 v[200:201], v[226:227], v[228:229]
	v_pk_fma_f32 v[82:83], v[30:31], s[2:3], v[82:83] op_sel_hi:[1,0,1]
	v_pk_fma_f32 v[80:81], v[28:29], s[2:3], v[80:81] op_sel_hi:[1,0,1]
	v_add_u32_e32 v253, 0xb0000, v252
	s_cmp_eq_u64 s[38:39], 0
	s_cbranch_scc0 .Lr8_plain
	global_load_dwordx4 v[16:19], v253, s[36:37] nt
	global_load_dwordx4 v[20:23], v253, s[36:37] offset:64 nt
	global_load_dwordx4 v[24:27], v253, s[36:37] offset:512 nt
	global_load_dwordx4 v[28:31], v253, s[36:37] offset:576 nt
	s_branch .Lr8_done

.Lr8_done:
	v_mul_f32_e32 v187, v82, v82
	v_mul_f32_e32 v173, v80, v80
	v_mul_f32_e32 v175, v81, v81
	v_mul_f32_e32 v231, v83, v83
	v_mov_b32_e32 v172, v80
	v_mov_b32_e32 v174, v81
	v_mov_b32_e32 v186, v82
	v_mov_b32_e32 v230, v83
	v_pk_add_f32 v[190:191], v[190:191], v[200:201]
	v_pk_add_f32 v[172:173], v[172:173], v[174:175]
	v_pk_add_f32 v[174:175], v[186:187], v[230:231]
	v_pk_add_f32 v[188:189], v[188:189], v[190:191]
	v_pk_add_f32 v[172:173], v[172:173], v[174:175]
	s_nop 0
	v_pk_add_f32 v[172:173], v[188:189], v[172:173]
	ds_bpermute_b32 v174, v194, v172
	ds_bpermute_b32 v175, v194, v173
	s_waitcnt lgkmcnt(0)
	v_pk_add_f32 v[172:173], v[172:173], v[174:175]
	ds_bpermute_b32 v174, v193, v172
	ds_bpermute_b32 v175, v193, v173
	s_and_saveexec_b64 s[2:3], vcc
	s_cbranch_execz .LBB0_341
	v_lshl_or_b32 v186, v199, 5, s4
	s_waitcnt lgkmcnt(0)
	v_pk_add_f32 v[172:173], v[172:173], v[174:175]
	ds_write_b64 v186, v[172:173]
